# dilated: XCD-aware block id permutation for KV halo L2 sharing
# speedup vs baseline: 1.0042x; 1.0042x over previous
.LBB0_679:
	s_cmpk_lg_i32 s83, 0x100
	s_cbranch_scc1 .Ldil_noremap
	s_and_b32 s0, s81, 7
	s_lshl_b32 s0, s0, 5
	s_lshr_b32 s1, s81, 3
	s_or_b32 s81, s0, s1
